# prompt MLA attention: next tile's V staged to the other LDS set mid-compute (after the row-max exchange), following V loads issued there; loop top = DMA wait + barrier + next K DMA only
# speedup vs baseline: 1.0104x; 1.0022x over previous
.Lkdma0_skip:
	v_add3_u32 v188, 0, v0, v2
	v_mov_b32_e32 v0, v1
	v_mov_b32_e32 v2, v1
	v_mov_b32_e32 v3, v1
	v_mov_b32_e32 v4, v1
	v_mov_b32_e32 v5, v1
	v_mov_b32_e32 v6, v1
	v_mov_b32_e32 v7, v1
	v_mov_b32_e32 v8, v1
	v_mov_b32_e32 v9, v1
	v_mov_b32_e32 v10, v1
	v_mov_b32_e32 v11, v1
	v_mov_b32_e32 v12, v1
	v_mov_b32_e32 v13, v1
	v_add_u32_e32 v189, v18, v19
	v_add_u32_e32 v190, v20, v21
	v_add_u32_e32 v191, v22, v23
	s_waitcnt vmcnt(3)
	v_add3_u32 v192, v17, v24, s12
	v_add3_u32 v193, v17, v16, s12
	v_add_u32_e32 v194, v25, v26
	v_mov_b64_e32 v[30:31], v[14:15]
	v_mov_b64_e32 v[46:47], v[14:15]
	v_mov_b64_e32 v[62:63], v[14:15]
	v_mov_b64_e32 v[78:79], v[14:15]
	s_sub_i32 s57, 64, s33
	s_mov_b32 s58, 0
	v_mov_b32_e32 v195, 0xf149f2ca
	v_mov_b32_e32 v184, 0
	v_mov_b64_e32 v[28:29], v[12:13]
	v_mov_b64_e32 v[26:27], v[10:11]
	v_mov_b64_e32 v[24:25], v[8:9]
	v_mov_b64_e32 v[22:23], v[6:7]
	v_mov_b64_e32 v[20:21], v[4:5]
	v_mov_b64_e32 v[18:19], v[2:3]
	v_mov_b64_e32 v[16:17], v[0:1]
	v_mov_b64_e32 v[44:45], v[12:13]
	v_mov_b64_e32 v[42:43], v[10:11]
	v_mov_b64_e32 v[40:41], v[8:9]
	v_mov_b64_e32 v[38:39], v[6:7]
	v_mov_b64_e32 v[36:37], v[4:5]
	v_mov_b64_e32 v[34:35], v[2:3]
	v_mov_b64_e32 v[32:33], v[0:1]
	v_mov_b64_e32 v[60:61], v[12:13]
	v_mov_b64_e32 v[58:59], v[10:11]
	v_mov_b64_e32 v[56:57], v[8:9]
	v_mov_b64_e32 v[54:55], v[6:7]
	v_mov_b64_e32 v[52:53], v[4:5]
	v_mov_b64_e32 v[50:51], v[2:3]
	v_mov_b64_e32 v[48:49], v[0:1]
	v_mov_b64_e32 v[76:77], v[12:13]
	v_mov_b64_e32 v[74:75], v[10:11]
	v_mov_b64_e32 v[72:73], v[8:9]
	v_mov_b64_e32 v[70:71], v[6:7]
	v_mov_b64_e32 v[68:69], v[4:5]
	v_mov_b64_e32 v[66:67], v[2:3]
	v_mov_b64_e32 v[64:65], v[0:1]
	s_waitcnt vmcnt(0)
	ds_write2_b64 v192, v[168:169], v[170:171] offset1:1
	ds_write2_b64 v193, v[164:165], v[166:167] offset1:1
	v_readlane_b32 s12, v253, 29
	v_readlane_b32 s13, v253, 30
	s_nop 3
	s_lshl_b64 s[12:13], s[12:13], 1
	s_nop 0
	v_lshl_add_u64 v[158:159], v[172:173], 0, s[12:13]
	v_lshl_add_u64 v[160:161], v[174:175], 0, s[12:13]
	global_load_dwordx4 v[168:171], v[158:159], off
	global_load_dwordx4 v[164:167], v[160:161], off
	s_branch .LBB0_556

.LBB0_556:
	s_cmp_ge_u32 s58, s27
	s_waitcnt vmcnt(2)
	s_waitcnt lgkmcnt(0)
	s_barrier
	s_cbranch_scc1 .LBB0_566
	v_readfirstlane_b32 s12, v152
	v_readfirstlane_b32 s13, v153
	v_readlane_b32 s22, v253, 29
	s_nop 3
	s_mul_i32 s23, s22, 0x140
	s_add_u32 s12, s12, s23
	s_addc_u32 s13, s13, 0
	s_xor_b32 s23, s98, 0x10000
	s_add_i32 s23, s23, s99
	s_mov_b32 m0, s23
	s_nop 0
	global_load_lds_dwordx4 v154, s[12:13]
	s_add_i32 m0, s23, 0x2000
	s_nop 0
	global_load_lds_dwordx4 v155, s[12:13]
	s_cmp_ge_u32 s99, 0x1400
	s_cbranch_scc1 .Lkdma_skip
	s_add_i32 m0, s23, 0x4000
	s_nop 0
	global_load_lds_dwordx4 v156, s[12:13]
.Lkdma_skip:
.LBB0_566:
	s_and_saveexec_b64 s[22:23], vcc
	s_cbranch_execz .LBB0_555
	ds_read_b128 v[196:199], v188
	ds_read_b128 v[202:205], v188 offset:32
	ds_read_b128 v[206:209], v188 offset:64
	ds_read_b128 v[210:213], v188 offset:96
	ds_read_b128 v[220:223], v188 offset:128
	ds_read_b128 v[224:227], v188 offset:160
	ds_read_b128 v[2:5], v188 offset:192
	ds_read_b128 v[6:9], v188 offset:224
	s_waitcnt lgkmcnt(7)
	v_mfma_f32_32x32x16_bf16 v[96:111], v[196:199], v[148:151], 0
	ds_read_b128 v[196:199], v188 offset:256
	s_waitcnt lgkmcnt(7)
	v_mfma_f32_32x32x16_bf16 v[96:111], v[202:205], v[144:147], v[96:111]
	ds_read_b128 v[202:205], v188 offset:288
	s_waitcnt lgkmcnt(7)
	v_mfma_f32_32x32x16_bf16 v[96:111], v[206:209], v[140:143], v[96:111]
	ds_read_b128 v[206:209], v188 offset:10752
	s_waitcnt lgkmcnt(7)
	v_mfma_f32_32x32x16_bf16 v[96:111], v[210:213], v[136:139], v[96:111]
	ds_read_b128 v[210:213], v188 offset:10784
	s_waitcnt lgkmcnt(7)
	v_mfma_f32_32x32x16_bf16 v[96:111], v[220:223], v[132:135], v[96:111]
	ds_read_b128 v[220:223], v188 offset:10816
	s_waitcnt lgkmcnt(7)
	v_mfma_f32_32x32x16_bf16 v[96:111], v[224:227], v[128:131], v[96:111]
	ds_read_b128 v[224:227], v188 offset:10848
	s_waitcnt lgkmcnt(7)
	v_mfma_f32_32x32x16_bf16 v[96:111], v[2:5], v[124:127], v[96:111]
	ds_read_b128 v[2:5], v188 offset:10880
	s_waitcnt lgkmcnt(7)
	v_mfma_f32_32x32x16_bf16 v[96:111], v[6:9], v[120:123], v[96:111]
	ds_read_b128 v[6:9], v188 offset:10912
	s_waitcnt lgkmcnt(7)
	v_mfma_f32_32x32x16_bf16 v[96:111], v[196:199], v[116:119], v[96:111]
	ds_read_b128 v[196:199], v188 offset:10944
	s_waitcnt lgkmcnt(7)
	v_mfma_f32_32x32x16_bf16 v[96:111], v[202:205], v[112:115], v[96:111]
	ds_read_b128 v[202:205], v188 offset:10976
	s_waitcnt lgkmcnt(7)
	v_mfma_f32_32x32x16_bf16 v[80:95], v[206:209], v[148:151], 0
	ds_read_b128 v[206:209], v188 offset:11008
	s_waitcnt lgkmcnt(7)
	v_mfma_f32_32x32x16_bf16 v[80:95], v[210:213], v[144:147], v[80:95]
	ds_read_b128 v[210:213], v188 offset:11040
	s_waitcnt lgkmcnt(7)
	v_mfma_f32_32x32x16_bf16 v[80:95], v[220:223], v[140:143], v[80:95]
	s_waitcnt lgkmcnt(6)
	v_mfma_f32_32x32x16_bf16 v[80:95], v[224:227], v[136:139], v[80:95]
	s_waitcnt lgkmcnt(5)
	v_mfma_f32_32x32x16_bf16 v[80:95], v[2:5], v[132:135], v[80:95]
	s_waitcnt lgkmcnt(4)
	v_mfma_f32_32x32x16_bf16 v[80:95], v[6:9], v[128:131], v[80:95]
	s_waitcnt lgkmcnt(3)
	v_mfma_f32_32x32x16_bf16 v[80:95], v[196:199], v[124:127], v[80:95]
	v_max_f32_e32 v0, v97, v97
	v_max_f32_e32 v10, v96, v96
	v_max_f32_e32 v0, v10, v0
	v_max3_f32 v0, v0, v98, v99
	v_max3_f32 v0, v0, v100, v101
	v_max3_f32 v0, v0, v102, v103
	v_max3_f32 v0, v0, v104, v105
	v_max3_f32 v0, v0, v106, v107
	v_max3_f32 v0, v0, v108, v109
	v_max3_f32 v0, v0, v110, v111
	v_and_b32_e32 v3, 64, v218
	v_xor_b32_e32 v2, 32, v218
	v_add_u32_e32 v3, 64, v3
	v_cmp_lt_i32_e64 s[12:13], v2, v3
	s_nop 1
	v_cndmask_b32_e64 v2, v218, v2, s[12:13]
	s_waitcnt lgkmcnt(2)
	v_mfma_f32_32x32x16_bf16 v[80:95], v[202:205], v[120:123], v[80:95]
	s_waitcnt lgkmcnt(1)
	v_mfma_f32_32x32x16_bf16 v[80:95], v[206:209], v[116:119], v[80:95]
	s_waitcnt lgkmcnt(0)
	v_mfma_f32_32x32x16_bf16 v[80:95], v[210:213], v[112:115], v[80:95]
	v_lshlrev_b32_e32 v2, 2, v2
	s_nop 10
	v_max3_f32 v0, v0, v80, v81
	v_max3_f32 v0, v0, v82, v83
	v_max3_f32 v0, v0, v84, v85
	v_max3_f32 v0, v0, v86, v87
	v_max3_f32 v0, v0, v88, v89
	v_max3_f32 v0, v0, v90, v91
	v_max3_f32 v0, v0, v92, v93
	v_max3_f32 v0, v0, v94, v95
	ds_bpermute_b32 v2, v2, v0
	s_waitcnt lgkmcnt(0)
	s_cmp_ge_u32 s58, s27
	s_cbranch_scc1 .Lvmid_skip
	s_waitcnt vmcnt(2)
	v_xor_b32_e32 v157, 0x10000, v192
	v_xor_b32_e32 v162, 0x10000, v193
	ds_write2_b64 v157, v[168:169], v[170:171] offset1:1
	ds_write2_b64 v162, v[164:165], v[166:167] offset1:1
.Lvmid_skip:
	v_readlane_b32 s12, v253, 29
	v_readlane_b32 s13, v253, 30
	s_nop 3
	s_add_u32 s12, s12, 64
	s_addc_u32 s13, s13, 0
	s_lshl_b64 s[12:13], s[12:13], 1
	s_nop 0
	v_lshl_add_u64 v[158:159], v[172:173], 0, s[12:13]
	v_lshl_add_u64 v[160:161], v[174:175], 0, s[12:13]
	global_load_dwordx4 v[168:171], v[158:159], off
	global_load_dwordx4 v[164:167], v[160:161], off
	v_add_u32_e32 v224, 0x5000, v194
	v_add_u32_e32 v225, 0x6000, v194
	v_add_u32_e32 v226, 0x7000, v194
	v_add_u32_e32 v227, 0x8000, v194
	ds_read2_b64 v[196:199], v224 offset0:128 offset1:130
	ds_read2_b64 v[202:205], v225 offset0:160 offset1:162
	ds_read2_b64 v[206:209], v226 offset0:192 offset1:194
	ds_read2_b64 v[210:213], v227 offset0:224 offset1:226
	ds_read2_b64 v[220:223], v224 offset0:132 offset1:134
	v_max3_f32 v0, v195, v0, v2
	v_sub_f32 v4, v97, v0
	v_sub_f32 v3, v96, v0
	v_sub_f32 v5, v100, v0
	v_sub_f32_e32 v2, v195, v0
	v_exp_f32_e32 v8, v4
	v_sub_f32 v4, v98, v0
	v_exp_f32_e32 v3, v3
	v_exp_f32_e32 v9, v4
	v_sub_f32 v4, v99, v0
	v_exp_f32_e32 v11, v5
	v_exp_f32_e32 v10, v4
	v_add_f32 v4, v1, v3
	v_sub_f32 v5, v101, v0
	v_exp_f32_e32 v2, v2
	v_add_f32 v4, v4, v8
	v_exp_f32_e32 v12, v5
	v_add_f32 v4, v4, v9
	v_sub_f32 v5, v102, v0
	v_cvt_pk_bf16_f32 v8, v3, v8
	v_add_f32 v4, v4, v10
	v_exp_f32_e32 v13, v5
	v_add_f32 v4, v4, v11
	v_sub_f32 v5, v103, v0
	v_add_f32 v4, v4, v12
	v_exp_f32_e32 v14, v5
	v_add_f32 v4, v4, v13
	v_cvt_pk_bf16_f32 v9, v9, v10
	v_add_f32 v96, v4, v14
	v_sub_f32 v4, v104, v0
	v_exp_f32_e32 v97, v4
	v_sub_f32 v4, v105, v0
	v_cvt_pk_bf16_f32 v10, v11, v12
	v_exp_f32_e32 v98, v4
	v_sub_f32 v4, v106, v0
	v_cvt_pk_bf16_f32 v11, v13, v14
	v_exp_f32_e32 v99, v4
	v_sub_f32 v4, v107, v0
	v_exp_f32_e32 v100, v4
	v_sub_f32 v4, v108, v0
	v_pk_mul_f32 v[64:65], v[64:65], v[2:3] op_sel_hi:[1,0]
	v_pk_mul_f32 v[66:67], v[66:67], v[2:3] op_sel_hi:[1,0]
	v_pk_mul_f32 v[68:69], v[68:69], v[2:3] op_sel_hi:[1,0]
	s_nop 0
	v_exp_f32_e32 v101, v4
	v_sub_f32 v4, v109, v0
	v_pk_mul_f32 v[70:71], v[70:71], v[2:3] op_sel_hi:[1,0]
	v_pk_mul_f32 v[72:73], v[72:73], v[2:3] op_sel_hi:[1,0]
	s_nop 0
	v_exp_f32_e32 v102, v4
	v_sub_f32 v4, v110, v0
	v_pk_mul_f32 v[74:75], v[74:75], v[2:3] op_sel_hi:[1,0]
	v_pk_mul_f32 v[76:77], v[76:77], v[2:3] op_sel_hi:[1,0]
	v_pk_mul_f32 v[78:79], v[78:79], v[2:3] op_sel_hi:[1,0]
	s_nop 0
	v_exp_f32_e32 v103, v4
	s_waitcnt lgkmcnt(4)
	v_mfma_f32_32x32x16_bf16 v[64:79], v[196:199], v[8:11], v[64:79]
	ds_read2_b64 v[196:199], v225 offset0:164 offset1:166
	v_pk_mul_f32 v[48:49], v[48:49], v[2:3] op_sel_hi:[1,0]
	v_pk_mul_f32 v[50:51], v[50:51], v[2:3] op_sel_hi:[1,0]
	v_pk_mul_f32 v[52:53], v[52:53], v[2:3] op_sel_hi:[1,0]
	v_pk_mul_f32 v[54:55], v[54:55], v[2:3] op_sel_hi:[1,0]
	v_pk_mul_f32 v[56:57], v[56:57], v[2:3] op_sel_hi:[1,0]
	v_pk_mul_f32 v[58:59], v[58:59], v[2:3] op_sel_hi:[1,0]
	v_pk_mul_f32 v[60:61], v[60:61], v[2:3] op_sel_hi:[1,0]
	v_pk_mul_f32 v[62:63], v[62:63], v[2:3] op_sel_hi:[1,0]
	s_waitcnt lgkmcnt(4)
	v_mfma_f32_32x32x16_bf16 v[48:63], v[202:205], v[8:11], v[48:63]
	ds_read2_b64 v[202:205], v226 offset0:196 offset1:198
	v_pk_mul_f32 v[32:33], v[32:33], v[2:3] op_sel_hi:[1,0]
	v_pk_mul_f32 v[34:35], v[34:35], v[2:3] op_sel_hi:[1,0]
	v_pk_mul_f32 v[36:37], v[36:37], v[2:3] op_sel_hi:[1,0]
	v_pk_mul_f32 v[38:39], v[38:39], v[2:3] op_sel_hi:[1,0]
	v_pk_mul_f32 v[40:41], v[40:41], v[2:3] op_sel_hi:[1,0]
	v_pk_mul_f32 v[42:43], v[42:43], v[2:3] op_sel_hi:[1,0]
	v_pk_mul_f32 v[44:45], v[44:45], v[2:3] op_sel_hi:[1,0]
	v_pk_mul_f32 v[46:47], v[46:47], v[2:3] op_sel_hi:[1,0]
	v_pk_mul_f32 v[16:17], v[16:17], v[2:3] op_sel_hi:[1,0]
	v_pk_mul_f32 v[18:19], v[18:19], v[2:3] op_sel_hi:[1,0]
	v_pk_mul_f32 v[20:21], v[20:21], v[2:3] op_sel_hi:[1,0]
	s_waitcnt lgkmcnt(4)
	v_mfma_f32_32x32x16_bf16 v[32:47], v[206:209], v[8:11], v[32:47]
	ds_read2_b64 v[206:209], v227 offset0:228 offset1:230
	v_pk_mul_f32 v[22:23], v[22:23], v[2:3] op_sel_hi:[1,0]
	v_pk_mul_f32 v[24:25], v[24:25], v[2:3] op_sel_hi:[1,0]
	v_pk_mul_f32 v[26:27], v[26:27], v[2:3] op_sel_hi:[1,0]
	v_pk_mul_f32 v[28:29], v[28:29], v[2:3] op_sel_hi:[1,0]
	v_pk_mul_f32 v[30:31], v[30:31], v[2:3] op_sel_hi:[1,0]
	v_mov_b32_e32 v195, v0
	s_waitcnt lgkmcnt(4)
	v_mfma_f32_32x32x16_bf16 v[16:31], v[210:213], v[8:11], v[16:31]
	ds_read2_b64 v[210:213], v224 offset0:136 offset1:138
	v_sub_f32 v8, v111, v0
	v_cvt_pk_bf16_f32 v9, v99, v100
	v_exp_f32_e32 v107, v8
	v_cvt_pk_bf16_f32 v8, v97, v98
	v_cvt_pk_bf16_f32 v10, v101, v102
	v_cvt_pk_bf16_f32 v11, v103, v107
	s_nop 0
	s_waitcnt lgkmcnt(4)
	v_mfma_f32_32x32x16_bf16 v[64:79], v[220:223], v[8:11], v[64:79]
	ds_read2_b64 v[220:223], v225 offset0:168 offset1:170
	v_add_f32 v4, v96, v97
	s_nop 0
	v_add_f32 v4, v4, v98
	s_nop 0
	v_add_f32 v4, v4, v99
	s_nop 0
	v_add_f32 v96, v4, v100
	v_sub_f32 v4, v80, v0
	s_waitcnt lgkmcnt(4)
	v_mfma_f32_32x32x16_bf16 v[48:63], v[196:199], v[8:11], v[48:63]
	ds_read2_b64 v[196:199], v226 offset0:200 offset1:202
	v_exp_f32_e32 v80, v4
	v_sub_f32 v12, v81, v0
	s_nop 0
	v_exp_f32_e32 v81, v12
	v_sub_f32 v12, v82, v0
	s_nop 0
	v_exp_f32_e32 v82, v12
	v_sub_f32 v12, v83, v0
	s_waitcnt lgkmcnt(4)
	v_mfma_f32_32x32x16_bf16 v[32:47], v[202:205], v[8:11], v[32:47]
	ds_read2_b64 v[202:205], v227 offset0:232 offset1:234
	v_exp_f32_e32 v83, v12
	v_sub_f32 v4, v84, v0
	s_nop 0
	v_exp_f32_e32 v84, v4
	v_sub_f32 v4, v85, v0
	s_nop 0
	v_exp_f32_e32 v85, v4
	v_sub_f32 v4, v86, v0
	s_waitcnt lgkmcnt(4)
	v_mfma_f32_32x32x16_bf16 v[16:31], v[206:209], v[8:11], v[16:31]
	ds_read2_b64 v[206:209], v224 offset0:140 offset1:142
	v_exp_f32_e32 v86, v4
	v_sub_f32 v8, v87, v0
	v_exp_f32_e32 v87, v8
	v_cvt_pk_bf16_f32 v8, v80, v81
	v_cvt_pk_bf16_f32 v9, v82, v83
	v_cvt_pk_bf16_f32 v10, v84, v85
	v_cvt_pk_bf16_f32 v11, v86, v87
	s_nop 0
	s_waitcnt lgkmcnt(4)
	v_mfma_f32_32x32x16_bf16 v[64:79], v[210:213], v[8:11], v[64:79]
	ds_read2_b64 v[210:213], v225 offset0:172 offset1:174
	v_add_f32 v4, v96, v101
	s_nop 0
	v_add_f32 v4, v4, v102
	s_nop 0
	v_add_f32 v4, v4, v103
	s_nop 0
	v_add_f32 v96, v4, v107
	v_sub_f32 v4, v88, v0
	s_waitcnt lgkmcnt(4)
	v_mfma_f32_32x32x16_bf16 v[48:63], v[220:223], v[8:11], v[48:63]
	ds_read2_b64 v[220:223], v226 offset0:204 offset1:206
	v_exp_f32_e32 v88, v4
	v_sub_f32 v12, v89, v0
	s_nop 0
	v_exp_f32_e32 v89, v12
	v_sub_f32 v12, v90, v0
	s_nop 0
	v_exp_f32_e32 v90, v12
	v_sub_f32 v12, v91, v0
	s_waitcnt lgkmcnt(4)
	v_mfma_f32_32x32x16_bf16 v[32:47], v[196:199], v[8:11], v[32:47]
	ds_read2_b64 v[196:199], v227 offset0:236 offset1:238
	v_exp_f32_e32 v91, v12
	v_sub_f32 v4, v92, v0
	s_nop 0
	v_exp_f32_e32 v92, v4
	v_sub_f32 v4, v93, v0
	s_nop 0
	v_exp_f32_e32 v93, v4
	v_sub_f32 v4, v94, v0
	s_waitcnt lgkmcnt(4)
	v_mfma_f32_32x32x16_bf16 v[16:31], v[202:205], v[8:11], v[16:31]
	v_exp_f32_e32 v94, v4
	v_sub_f32 v8, v95, v0
	v_cvt_pk_bf16_f32 v9, v90, v91
	v_exp_f32_e32 v95, v8
	v_cvt_pk_bf16_f32 v8, v88, v89
	v_cvt_pk_bf16_f32 v10, v92, v93
	v_add_f32 v3, v96, v80
	v_cvt_pk_bf16_f32 v11, v94, v95
	v_add_f32 v3, v3, v81
	s_nop 0
	v_add_f32 v3, v3, v82
	s_waitcnt lgkmcnt(3)
	v_mfma_f32_32x32x16_bf16 v[64:79], v[206:209], v[8:11], v[64:79]
	v_add_f32 v3, v3, v83
	s_nop 0
	v_add_f32 v3, v3, v84
	s_nop 0
	v_add_f32 v3, v3, v85
	s_waitcnt lgkmcnt(2)
	v_mfma_f32_32x32x16_bf16 v[48:63], v[210:213], v[8:11], v[48:63]
	v_add_f32 v3, v3, v86
	s_nop 0
	v_add_f32 v3, v3, v87
	s_nop 0
	v_add_f32 v3, v3, v88
	s_nop 0
	v_add_f32 v3, v3, v89
	s_waitcnt lgkmcnt(1)
	v_mfma_f32_32x32x16_bf16 v[32:47], v[220:223], v[8:11], v[32:47]
	v_add_f32 v3, v3, v90
	s_nop 0
	v_add_f32 v3, v3, v91
	s_nop 0
	v_add_f32 v3, v3, v92
	s_nop 0
	v_add_f32 v3, v3, v93
	s_waitcnt lgkmcnt(0)
	v_mfma_f32_32x32x16_bf16 v[16:31], v[196:199], v[8:11], v[16:31]
	v_add_f32 v3, v3, v94
	s_nop 0
	v_add_f32 v3, v3, v95
	s_nop 0
	v_fmac_f32_e32 v3, v184, v2
	v_mov_b32_e32 v184, v3
	s_branch .LBB0_555
